# scan: LDS waitcnt instructions coalesced (79 -> 17 per 8-token chunk)
# speedup vs baseline: 1.0038x; 1.0038x over previous
.Lscan_nored:
	s_waitcnt lgkmcnt(1)
	v_pk_mul_f32 v[86:87], v[2:3], v[38:39]
	v_pk_mul_f32 v[78:79], v[2:3], v[34:35]
	v_pk_fma_f32 v[86:87], v[4:5], v[40:41], v[86:87]
	v_pk_mul_f32 v[80:81], v[4:5], v[36:37]
	ds_read_b128 v[38:41], v110 offset:4608
	v_add_f32_e32 v90, v86, v87
	v_pk_fma_f32 v[82:83], v[54:55], v[46:47], v[78:79] op_sel_hi:[0,1,1]
	ds_read_b128 v[34:37], v110 offset:512
	v_add_f32_dpp v90, v90, v90 quad_perm:[1,0,3,2] row_mask:0xf bank_mask:0xf bound_ctrl:1
	v_pk_fma_f32 v[84:85], v[54:55], v[48:49], v[80:81] op_sel_hi:[0,1,1]
	ds_read_b128 v[46:49], v110 offset:12800
	v_add_f32_dpp v90, v90, v90 quad_perm:[2,3,0,1] row_mask:0xf bank_mask:0xf bound_ctrl:1
	ds_read_b32 v54, v111 offset:20992
	s_nop 0
	v_add_f32_dpp v90, v90, v90 row_half_mirror row_mask:0xf bank_mask:0xf bound_ctrl:1
	s_nop 0
	s_nop 0
	v_add_f32_dpp v92, v90, v90 row_mirror row_mask:0xf bank_mask:0xf bound_ctrl:1
	v_pk_fma_f32 v[2:3], v[92:93], v[42:43], v[82:83] op_sel_hi:[0,1,1] neg_lo:[1,0,0] neg_hi:[1,0,0]
	v_pk_fma_f32 v[4:5], v[92:93], v[44:45], v[84:85] op_sel_hi:[0,1,1] neg_lo:[1,0,0] neg_hi:[1,0,0]
	ds_read_b128 v[42:45], v110 offset:8704
	v_pk_mul_f32 v[86:87], v[2:3], v[60:61]
	v_pk_mul_f32 v[78:79], v[2:3], v[56:57]
	v_pk_fma_f32 v[86:87], v[4:5], v[62:63], v[86:87]
	v_pk_mul_f32 v[80:81], v[4:5], v[58:59]
	v_pk_mul_f32 v[88:89], v[2:3], v[50:51]
	v_add_f32_e32 v90, v86, v87
	v_pk_fma_f32 v[82:83], v[76:77], v[68:69], v[78:79] op_sel_hi:[0,1,1]
	v_pk_fma_f32 v[88:89], v[4:5], v[52:53], v[88:89]
	v_add_f32_dpp v90, v90, v90 quad_perm:[1,0,3,2] row_mask:0xf bank_mask:0xf bound_ctrl:1
	v_pk_fma_f32 v[84:85], v[76:77], v[70:71], v[80:81] op_sel_hi:[0,1,1]
	ds_read_b128 v[60:63], v110 offset:4864
	v_add_f32_dpp v90, v90, v90 quad_perm:[2,3,0,1] row_mask:0xf bank_mask:0xf bound_ctrl:1
	ds_read_b128 v[56:59], v110 offset:768
	v_add_f32_e32 v94, v88, v89
	v_add_f32_dpp v90, v90, v90 row_half_mirror row_mask:0xf bank_mask:0xf bound_ctrl:1
	ds_read_b128 v[50:53], v110 offset:16896
	ds_read_b128 v[68:71], v110 offset:13056
	v_add_f32_dpp v92, v90, v90 row_mirror row_mask:0xf bank_mask:0xf bound_ctrl:1
	ds_read_b32 v76, v111 offset:21248
	v_pk_fma_f32 v[2:3], v[92:93], v[64:65], v[82:83] op_sel_hi:[0,1,1] neg_lo:[1,0,0] neg_hi:[1,0,0]
	v_pk_fma_f32 v[4:5], v[92:93], v[66:67], v[84:85] op_sel_hi:[0,1,1] neg_lo:[1,0,0] neg_hi:[1,0,0]
	ds_read_b128 v[64:67], v110 offset:8960
	s_waitcnt lgkmcnt(6)
	v_pk_mul_f32 v[86:87], v[2:3], v[38:39]
	v_pk_mul_f32 v[78:79], v[2:3], v[34:35]
	v_pk_fma_f32 v[86:87], v[4:5], v[40:41], v[86:87]
	v_pk_mul_f32 v[80:81], v[4:5], v[36:37]
	v_pk_mul_f32 v[88:89], v[2:3], v[72:73]
	v_add_f32_e32 v90, v86, v87
	v_pk_fma_f32 v[82:83], v[54:55], v[46:47], v[78:79] op_sel_hi:[0,1,1]
	v_pk_fma_f32 v[88:89], v[4:5], v[74:75], v[88:89]
	v_add_f32_dpp v90, v90, v90 quad_perm:[1,0,3,2] row_mask:0xf bank_mask:0xf bound_ctrl:1
	v_pk_fma_f32 v[84:85], v[54:55], v[48:49], v[80:81] op_sel_hi:[0,1,1]
	ds_read_b128 v[38:41], v110 offset:5120
	v_add_f32_dpp v90, v90, v90 quad_perm:[2,3,0,1] row_mask:0xf bank_mask:0xf bound_ctrl:1
	ds_read_b128 v[34:37], v110 offset:1024
	v_add_f32_e32 v95, v88, v89
	v_add_f32_dpp v90, v90, v90 row_half_mirror row_mask:0xf bank_mask:0xf bound_ctrl:1
	ds_read_b128 v[72:75], v110 offset:17152
	ds_read_b128 v[46:49], v110 offset:13312
	v_add_f32_dpp v92, v90, v90 row_mirror row_mask:0xf bank_mask:0xf bound_ctrl:1
	ds_read_b32 v54, v111 offset:21504
	v_pk_fma_f32 v[2:3], v[92:93], v[42:43], v[82:83] op_sel_hi:[0,1,1] neg_lo:[1,0,0] neg_hi:[1,0,0]
	v_pk_fma_f32 v[4:5], v[92:93], v[44:45], v[84:85] op_sel_hi:[0,1,1] neg_lo:[1,0,0] neg_hi:[1,0,0]
	ds_read_b128 v[42:45], v110 offset:9216
	s_waitcnt lgkmcnt(6)
	v_pk_mul_f32 v[86:87], v[2:3], v[60:61]
	v_pk_mul_f32 v[78:79], v[2:3], v[56:57]
	v_pk_fma_f32 v[86:87], v[4:5], v[62:63], v[86:87]
	v_pk_mul_f32 v[80:81], v[4:5], v[58:59]
	v_pk_mul_f32 v[88:89], v[2:3], v[50:51]
	v_add_f32_e32 v90, v86, v87
	v_pk_fma_f32 v[82:83], v[76:77], v[68:69], v[78:79] op_sel_hi:[0,1,1]
	v_pk_fma_f32 v[88:89], v[4:5], v[52:53], v[88:89]
	v_add_f32_dpp v90, v90, v90 quad_perm:[1,0,3,2] row_mask:0xf bank_mask:0xf bound_ctrl:1
	v_pk_fma_f32 v[84:85], v[76:77], v[70:71], v[80:81] op_sel_hi:[0,1,1]
	ds_read_b128 v[60:63], v110 offset:5376
	v_add_f32_dpp v90, v90, v90 quad_perm:[2,3,0,1] row_mask:0xf bank_mask:0xf bound_ctrl:1
	ds_read_b128 v[56:59], v110 offset:1280
	v_add_f32_e32 v96, v88, v89
	v_add_f32_dpp v90, v90, v90 row_half_mirror row_mask:0xf bank_mask:0xf bound_ctrl:1
	ds_read_b128 v[50:53], v110 offset:17408
	ds_read_b128 v[68:71], v110 offset:13568
	v_add_f32_dpp v92, v90, v90 row_mirror row_mask:0xf bank_mask:0xf bound_ctrl:1
	ds_read_b32 v76, v111 offset:21760
	v_pk_fma_f32 v[2:3], v[92:93], v[64:65], v[82:83] op_sel_hi:[0,1,1] neg_lo:[1,0,0] neg_hi:[1,0,0]
	v_pk_fma_f32 v[4:5], v[92:93], v[66:67], v[84:85] op_sel_hi:[0,1,1] neg_lo:[1,0,0] neg_hi:[1,0,0]
	ds_read_b128 v[64:67], v110 offset:9472
	s_waitcnt lgkmcnt(6)
	v_pk_mul_f32 v[86:87], v[2:3], v[38:39]
	v_pk_mul_f32 v[78:79], v[2:3], v[34:35]
	v_pk_fma_f32 v[86:87], v[4:5], v[40:41], v[86:87]
	v_pk_mul_f32 v[80:81], v[4:5], v[36:37]
	v_pk_mul_f32 v[88:89], v[2:3], v[72:73]
	v_add_f32_e32 v90, v86, v87
	v_pk_fma_f32 v[82:83], v[54:55], v[46:47], v[78:79] op_sel_hi:[0,1,1]
	v_pk_fma_f32 v[88:89], v[4:5], v[74:75], v[88:89]
	v_add_f32_dpp v90, v90, v90 quad_perm:[1,0,3,2] row_mask:0xf bank_mask:0xf bound_ctrl:1
	v_pk_fma_f32 v[84:85], v[54:55], v[48:49], v[80:81] op_sel_hi:[0,1,1]
	ds_read_b128 v[38:41], v110 offset:5632
	v_add_f32_dpp v90, v90, v90 quad_perm:[2,3,0,1] row_mask:0xf bank_mask:0xf bound_ctrl:1
	ds_read_b128 v[34:37], v110 offset:1536
	v_add_f32_e32 v97, v88, v89
	v_add_f32_dpp v90, v90, v90 row_half_mirror row_mask:0xf bank_mask:0xf bound_ctrl:1
	ds_read_b128 v[72:75], v110 offset:17664
	ds_read_b128 v[46:49], v110 offset:13824
	v_add_f32_dpp v92, v90, v90 row_mirror row_mask:0xf bank_mask:0xf bound_ctrl:1
	ds_read_b32 v54, v111 offset:22016
	v_pk_fma_f32 v[2:3], v[92:93], v[42:43], v[82:83] op_sel_hi:[0,1,1] neg_lo:[1,0,0] neg_hi:[1,0,0]
	v_pk_fma_f32 v[4:5], v[92:93], v[44:45], v[84:85] op_sel_hi:[0,1,1] neg_lo:[1,0,0] neg_hi:[1,0,0]
	ds_read_b128 v[42:45], v110 offset:9728
	s_waitcnt lgkmcnt(6)
	v_pk_mul_f32 v[86:87], v[2:3], v[60:61]
	v_pk_mul_f32 v[78:79], v[2:3], v[56:57]
	v_pk_fma_f32 v[86:87], v[4:5], v[62:63], v[86:87]
	v_pk_mul_f32 v[80:81], v[4:5], v[58:59]
	v_pk_mul_f32 v[88:89], v[2:3], v[50:51]
	v_add_f32_e32 v90, v86, v87
	v_pk_fma_f32 v[82:83], v[76:77], v[68:69], v[78:79] op_sel_hi:[0,1,1]
	v_pk_fma_f32 v[88:89], v[4:5], v[52:53], v[88:89]
	v_add_f32_dpp v90, v90, v90 quad_perm:[1,0,3,2] row_mask:0xf bank_mask:0xf bound_ctrl:1
	v_pk_fma_f32 v[84:85], v[76:77], v[70:71], v[80:81] op_sel_hi:[0,1,1]
	ds_read_b128 v[60:63], v110 offset:5888
	v_add_f32_dpp v90, v90, v90 quad_perm:[2,3,0,1] row_mask:0xf bank_mask:0xf bound_ctrl:1
	ds_read_b128 v[56:59], v110 offset:1792
	v_add_f32_e32 v98, v88, v89
	v_add_f32_dpp v90, v90, v90 row_half_mirror row_mask:0xf bank_mask:0xf bound_ctrl:1
	ds_read_b128 v[50:53], v110 offset:17920
	ds_read_b128 v[68:71], v110 offset:14080
	v_add_f32_dpp v92, v90, v90 row_mirror row_mask:0xf bank_mask:0xf bound_ctrl:1
	ds_read_b32 v76, v111 offset:22272
	v_pk_fma_f32 v[2:3], v[92:93], v[64:65], v[82:83] op_sel_hi:[0,1,1] neg_lo:[1,0,0] neg_hi:[1,0,0]
	v_pk_fma_f32 v[4:5], v[92:93], v[66:67], v[84:85] op_sel_hi:[0,1,1] neg_lo:[1,0,0] neg_hi:[1,0,0]
	ds_read_b128 v[64:67], v110 offset:9984
	s_waitcnt lgkmcnt(6)
	v_pk_mul_f32 v[86:87], v[2:3], v[38:39]
	v_pk_mul_f32 v[78:79], v[2:3], v[34:35]
	v_pk_fma_f32 v[86:87], v[4:5], v[40:41], v[86:87]
	v_pk_mul_f32 v[80:81], v[4:5], v[36:37]
	v_pk_mul_f32 v[88:89], v[2:3], v[72:73]
	v_add_f32_e32 v90, v86, v87
	v_pk_fma_f32 v[82:83], v[54:55], v[46:47], v[78:79] op_sel_hi:[0,1,1]
	v_pk_fma_f32 v[88:89], v[4:5], v[74:75], v[88:89]
	v_add_f32_dpp v90, v90, v90 quad_perm:[1,0,3,2] row_mask:0xf bank_mask:0xf bound_ctrl:1
	v_pk_fma_f32 v[84:85], v[54:55], v[48:49], v[80:81] op_sel_hi:[0,1,1]
	ds_read_b128 v[38:41], v110 offset:6144
	v_add_f32_dpp v90, v90, v90 quad_perm:[2,3,0,1] row_mask:0xf bank_mask:0xf bound_ctrl:1
	ds_read_b128 v[34:37], v110 offset:2048
	v_add_f32_e32 v99, v88, v89
	v_add_f32_dpp v90, v90, v90 row_half_mirror row_mask:0xf bank_mask:0xf bound_ctrl:1
	ds_read_b128 v[72:75], v110 offset:18176
	ds_read_b128 v[46:49], v110 offset:14336
	v_add_f32_dpp v92, v90, v90 row_mirror row_mask:0xf bank_mask:0xf bound_ctrl:1
	ds_read_b32 v54, v111 offset:22528
	v_pk_fma_f32 v[2:3], v[92:93], v[42:43], v[82:83] op_sel_hi:[0,1,1] neg_lo:[1,0,0] neg_hi:[1,0,0]
	v_pk_fma_f32 v[4:5], v[92:93], v[44:45], v[84:85] op_sel_hi:[0,1,1] neg_lo:[1,0,0] neg_hi:[1,0,0]
	ds_read_b128 v[42:45], v110 offset:10240
	s_waitcnt lgkmcnt(6)
	v_pk_mul_f32 v[86:87], v[2:3], v[60:61]
	v_pk_mul_f32 v[78:79], v[2:3], v[56:57]
	v_pk_fma_f32 v[86:87], v[4:5], v[62:63], v[86:87]
	v_pk_mul_f32 v[80:81], v[4:5], v[58:59]
	v_pk_mul_f32 v[88:89], v[2:3], v[50:51]
	v_add_f32_e32 v90, v86, v87
	v_pk_fma_f32 v[82:83], v[76:77], v[68:69], v[78:79] op_sel_hi:[0,1,1]
	v_pk_fma_f32 v[88:89], v[4:5], v[52:53], v[88:89]
	v_add_f32_dpp v90, v90, v90 quad_perm:[1,0,3,2] row_mask:0xf bank_mask:0xf bound_ctrl:1
	v_pk_fma_f32 v[84:85], v[76:77], v[70:71], v[80:81] op_sel_hi:[0,1,1]
	ds_read_b128 v[60:63], v110 offset:6400
	v_add_f32_dpp v90, v90, v90 quad_perm:[2,3,0,1] row_mask:0xf bank_mask:0xf bound_ctrl:1
	ds_read_b128 v[56:59], v110 offset:2304
	v_add_f32_e32 v100, v88, v89
	v_add_f32_dpp v90, v90, v90 row_half_mirror row_mask:0xf bank_mask:0xf bound_ctrl:1
	ds_read_b128 v[50:53], v110 offset:18432
	ds_read_b128 v[68:71], v110 offset:14592
	v_add_f32_dpp v92, v90, v90 row_mirror row_mask:0xf bank_mask:0xf bound_ctrl:1
	ds_read_b32 v76, v111 offset:22784
	v_pk_fma_f32 v[2:3], v[92:93], v[64:65], v[82:83] op_sel_hi:[0,1,1] neg_lo:[1,0,0] neg_hi:[1,0,0]
	v_pk_fma_f32 v[4:5], v[92:93], v[66:67], v[84:85] op_sel_hi:[0,1,1] neg_lo:[1,0,0] neg_hi:[1,0,0]
	ds_read_b128 v[64:67], v110 offset:10496
	s_waitcnt lgkmcnt(6)
	v_pk_mul_f32 v[86:87], v[2:3], v[38:39]
	v_pk_mul_f32 v[78:79], v[2:3], v[34:35]
	v_pk_fma_f32 v[86:87], v[4:5], v[40:41], v[86:87]
	v_pk_mul_f32 v[80:81], v[4:5], v[36:37]
	v_pk_mul_f32 v[88:89], v[2:3], v[72:73]
	v_add_f32_e32 v90, v86, v87
	v_pk_fma_f32 v[82:83], v[54:55], v[46:47], v[78:79] op_sel_hi:[0,1,1]
	v_pk_fma_f32 v[88:89], v[4:5], v[74:75], v[88:89]
	v_add_f32_dpp v90, v90, v90 quad_perm:[1,0,3,2] row_mask:0xf bank_mask:0xf bound_ctrl:1
	v_pk_fma_f32 v[84:85], v[54:55], v[48:49], v[80:81] op_sel_hi:[0,1,1]
	ds_read_b128 v[38:41], v110 offset:6656
	v_add_f32_dpp v90, v90, v90 quad_perm:[2,3,0,1] row_mask:0xf bank_mask:0xf bound_ctrl:1
	ds_read_b128 v[34:37], v110 offset:2560
	v_add_f32_e32 v101, v88, v89
	v_add_f32_dpp v90, v90, v90 row_half_mirror row_mask:0xf bank_mask:0xf bound_ctrl:1
	ds_read_b128 v[72:75], v110 offset:18688
	ds_read_b128 v[46:49], v110 offset:14848
	v_add_f32_dpp v92, v90, v90 row_mirror row_mask:0xf bank_mask:0xf bound_ctrl:1
	ds_read_b32 v54, v111 offset:23040
	v_pk_fma_f32 v[2:3], v[92:93], v[42:43], v[82:83] op_sel_hi:[0,1,1] neg_lo:[1,0,0] neg_hi:[1,0,0]
	v_pk_fma_f32 v[4:5], v[92:93], v[44:45], v[84:85] op_sel_hi:[0,1,1] neg_lo:[1,0,0] neg_hi:[1,0,0]
	ds_read_b128 v[42:45], v110 offset:10752
	s_waitcnt lgkmcnt(6)
	v_pk_mul_f32 v[86:87], v[2:3], v[60:61]
	v_pk_mul_f32 v[78:79], v[2:3], v[56:57]
	v_pk_fma_f32 v[86:87], v[4:5], v[62:63], v[86:87]
	v_pk_mul_f32 v[80:81], v[4:5], v[58:59]
	v_pk_mul_f32 v[88:89], v[2:3], v[50:51]
	v_add_f32_e32 v90, v86, v87
	v_pk_fma_f32 v[82:83], v[76:77], v[68:69], v[78:79] op_sel_hi:[0,1,1]
	v_pk_fma_f32 v[88:89], v[4:5], v[52:53], v[88:89]
	v_add_f32_dpp v90, v90, v90 quad_perm:[1,0,3,2] row_mask:0xf bank_mask:0xf bound_ctrl:1
	v_pk_fma_f32 v[84:85], v[76:77], v[70:71], v[80:81] op_sel_hi:[0,1,1]
	ds_read_b128 v[60:63], v110 offset:6912
	v_add_f32_dpp v90, v90, v90 quad_perm:[2,3,0,1] row_mask:0xf bank_mask:0xf bound_ctrl:1
	ds_read_b128 v[56:59], v110 offset:2816
	v_add_f32_e32 v102, v88, v89
	v_add_f32_dpp v90, v90, v90 row_half_mirror row_mask:0xf bank_mask:0xf bound_ctrl:1
	ds_read_b128 v[50:53], v110 offset:18944
	ds_read_b128 v[68:71], v110 offset:15104
	v_add_f32_dpp v92, v90, v90 row_mirror row_mask:0xf bank_mask:0xf bound_ctrl:1
	ds_read_b32 v76, v111 offset:23296
	v_pk_fma_f32 v[2:3], v[92:93], v[64:65], v[82:83] op_sel_hi:[0,1,1] neg_lo:[1,0,0] neg_hi:[1,0,0]
	v_pk_fma_f32 v[4:5], v[92:93], v[66:67], v[84:85] op_sel_hi:[0,1,1] neg_lo:[1,0,0] neg_hi:[1,0,0]
	ds_read_b128 v[64:67], v110 offset:11008
	s_waitcnt lgkmcnt(6)
	v_pk_mul_f32 v[86:87], v[2:3], v[38:39]
	v_pk_mul_f32 v[78:79], v[2:3], v[34:35]
	v_pk_fma_f32 v[86:87], v[4:5], v[40:41], v[86:87]
	v_pk_mul_f32 v[80:81], v[4:5], v[36:37]
	v_pk_mul_f32 v[88:89], v[2:3], v[72:73]
	v_add_f32_e32 v90, v86, v87
	v_pk_fma_f32 v[82:83], v[54:55], v[46:47], v[78:79] op_sel_hi:[0,1,1]
	v_pk_fma_f32 v[88:89], v[4:5], v[74:75], v[88:89]
	v_add_f32_dpp v90, v90, v90 quad_perm:[1,0,3,2] row_mask:0xf bank_mask:0xf bound_ctrl:1
	v_pk_fma_f32 v[84:85], v[54:55], v[48:49], v[80:81] op_sel_hi:[0,1,1]
	ds_read_b128 v[38:41], v110 offset:7168
	v_add_f32_dpp v90, v90, v90 quad_perm:[2,3,0,1] row_mask:0xf bank_mask:0xf bound_ctrl:1
	ds_read_b128 v[34:37], v110 offset:3072
	v_add_f32_e32 v103, v88, v89
	v_add_f32_dpp v90, v90, v90 row_half_mirror row_mask:0xf bank_mask:0xf bound_ctrl:1
	ds_read_b128 v[72:75], v110 offset:19200
	ds_read_b128 v[46:49], v110 offset:15360
	v_add_f32_dpp v92, v90, v90 row_mirror row_mask:0xf bank_mask:0xf bound_ctrl:1
	ds_read_b32 v54, v111 offset:23552
	v_pk_fma_f32 v[2:3], v[92:93], v[42:43], v[82:83] op_sel_hi:[0,1,1] neg_lo:[1,0,0] neg_hi:[1,0,0]
	v_pk_fma_f32 v[4:5], v[92:93], v[44:45], v[84:85] op_sel_hi:[0,1,1] neg_lo:[1,0,0] neg_hi:[1,0,0]
	ds_read_b128 v[42:45], v110 offset:11264
	s_waitcnt lgkmcnt(6)
	v_pk_mul_f32 v[86:87], v[2:3], v[60:61]
	v_pk_mul_f32 v[78:79], v[2:3], v[56:57]
	v_pk_fma_f32 v[86:87], v[4:5], v[62:63], v[86:87]
	v_pk_mul_f32 v[80:81], v[4:5], v[58:59]
	v_pk_mul_f32 v[88:89], v[2:3], v[50:51]
	v_add_f32_e32 v90, v86, v87
	v_pk_fma_f32 v[82:83], v[76:77], v[68:69], v[78:79] op_sel_hi:[0,1,1]
	v_pk_fma_f32 v[88:89], v[4:5], v[52:53], v[88:89]
	v_add_f32_dpp v90, v90, v90 quad_perm:[1,0,3,2] row_mask:0xf bank_mask:0xf bound_ctrl:1
	v_pk_fma_f32 v[84:85], v[76:77], v[70:71], v[80:81] op_sel_hi:[0,1,1]
	ds_read_b128 v[60:63], v110 offset:7424
	v_add_f32_dpp v90, v90, v90 quad_perm:[2,3,0,1] row_mask:0xf bank_mask:0xf bound_ctrl:1
	ds_read_b128 v[56:59], v110 offset:3328
	v_add_f32_e32 v104, v88, v89
	v_add_f32_dpp v90, v90, v90 row_half_mirror row_mask:0xf bank_mask:0xf bound_ctrl:1
	ds_read_b128 v[50:53], v110 offset:19456
	ds_read_b128 v[68:71], v110 offset:15616
	v_add_f32_dpp v92, v90, v90 row_mirror row_mask:0xf bank_mask:0xf bound_ctrl:1
	ds_read_b32 v76, v111 offset:23808
	v_pk_fma_f32 v[2:3], v[92:93], v[64:65], v[82:83] op_sel_hi:[0,1,1] neg_lo:[1,0,0] neg_hi:[1,0,0]
	v_pk_fma_f32 v[4:5], v[92:93], v[66:67], v[84:85] op_sel_hi:[0,1,1] neg_lo:[1,0,0] neg_hi:[1,0,0]
	ds_read_b128 v[64:67], v110 offset:11520
	s_waitcnt lgkmcnt(6)
	v_pk_mul_f32 v[86:87], v[2:3], v[38:39]
	v_pk_mul_f32 v[78:79], v[2:3], v[34:35]
	v_pk_fma_f32 v[86:87], v[4:5], v[40:41], v[86:87]
	v_pk_mul_f32 v[80:81], v[4:5], v[36:37]
	v_pk_mul_f32 v[88:89], v[2:3], v[72:73]
	v_add_f32_e32 v90, v86, v87
	v_pk_fma_f32 v[82:83], v[54:55], v[46:47], v[78:79] op_sel_hi:[0,1,1]
	v_pk_fma_f32 v[88:89], v[4:5], v[74:75], v[88:89]
	v_add_f32_dpp v90, v90, v90 quad_perm:[1,0,3,2] row_mask:0xf bank_mask:0xf bound_ctrl:1
	v_pk_fma_f32 v[84:85], v[54:55], v[48:49], v[80:81] op_sel_hi:[0,1,1]
	ds_read_b128 v[38:41], v110 offset:7680
	v_add_f32_dpp v90, v90, v90 quad_perm:[2,3,0,1] row_mask:0xf bank_mask:0xf bound_ctrl:1
	ds_read_b128 v[34:37], v110 offset:3584
	v_add_f32_e32 v105, v88, v89
	v_add_f32_dpp v90, v90, v90 row_half_mirror row_mask:0xf bank_mask:0xf bound_ctrl:1
	ds_read_b128 v[72:75], v110 offset:19712
	ds_read_b128 v[46:49], v110 offset:15872
	v_add_f32_dpp v92, v90, v90 row_mirror row_mask:0xf bank_mask:0xf bound_ctrl:1
	ds_read_b32 v54, v111 offset:24064
	v_pk_fma_f32 v[2:3], v[92:93], v[42:43], v[82:83] op_sel_hi:[0,1,1] neg_lo:[1,0,0] neg_hi:[1,0,0]
	v_pk_fma_f32 v[4:5], v[92:93], v[44:45], v[84:85] op_sel_hi:[0,1,1] neg_lo:[1,0,0] neg_hi:[1,0,0]
	ds_read_b128 v[42:45], v110 offset:11776
	s_waitcnt lgkmcnt(6)
	v_pk_mul_f32 v[86:87], v[2:3], v[60:61]
	v_pk_mul_f32 v[78:79], v[2:3], v[56:57]
	v_pk_fma_f32 v[86:87], v[4:5], v[62:63], v[86:87]
	v_pk_mul_f32 v[80:81], v[4:5], v[58:59]
	v_pk_mul_f32 v[88:89], v[2:3], v[50:51]
	v_add_f32_e32 v90, v86, v87
	v_pk_fma_f32 v[82:83], v[76:77], v[68:69], v[78:79] op_sel_hi:[0,1,1]
	v_pk_fma_f32 v[88:89], v[4:5], v[52:53], v[88:89]
	v_add_f32_dpp v90, v90, v90 quad_perm:[1,0,3,2] row_mask:0xf bank_mask:0xf bound_ctrl:1
	v_pk_fma_f32 v[84:85], v[76:77], v[70:71], v[80:81] op_sel_hi:[0,1,1]
	ds_read_b128 v[60:63], v110 offset:7936
	v_add_f32_dpp v90, v90, v90 quad_perm:[2,3,0,1] row_mask:0xf bank_mask:0xf bound_ctrl:1
	ds_read_b128 v[56:59], v110 offset:3840
	v_add_f32_e32 v106, v88, v89
	v_add_f32_dpp v90, v90, v90 row_half_mirror row_mask:0xf bank_mask:0xf bound_ctrl:1
	ds_read_b128 v[50:53], v110 offset:19968
	ds_read_b128 v[68:71], v110 offset:16128
	v_add_f32_dpp v92, v90, v90 row_mirror row_mask:0xf bank_mask:0xf bound_ctrl:1
	ds_read_b32 v76, v111 offset:24320
	s_cmpk_eq_i32 s33, 0x10f
	s_cbranch_scc1 .Lscan_tail_last
	v_pk_fma_f32 v[2:3], v[92:93], v[64:65], v[82:83] op_sel_hi:[0,1,1] neg_lo:[1,0,0] neg_hi:[1,0,0]
	v_pk_fma_f32 v[4:5], v[92:93], v[66:67], v[84:85] op_sel_hi:[0,1,1] neg_lo:[1,0,0] neg_hi:[1,0,0]
	ds_read_b128 v[64:67], v110 offset:12032
	s_waitcnt lgkmcnt(6)
	v_pk_mul_f32 v[86:87], v[2:3], v[38:39]
	v_pk_mul_f32 v[78:79], v[2:3], v[34:35]
	v_pk_fma_f32 v[86:87], v[4:5], v[40:41], v[86:87]
	v_pk_mul_f32 v[80:81], v[4:5], v[36:37]
	v_pk_mul_f32 v[88:89], v[2:3], v[72:73]
	v_add_f32_e32 v90, v86, v87
	v_pk_fma_f32 v[82:83], v[54:55], v[46:47], v[78:79] op_sel_hi:[0,1,1]
	v_pk_fma_f32 v[88:89], v[4:5], v[74:75], v[88:89]
	v_add_f32_dpp v90, v90, v90 quad_perm:[1,0,3,2] row_mask:0xf bank_mask:0xf bound_ctrl:1
	v_pk_fma_f32 v[84:85], v[54:55], v[48:49], v[80:81] op_sel_hi:[0,1,1]
	s_waitcnt vmcnt(0)
	v_add_f32_dpp v90, v90, v90 quad_perm:[2,3,0,1] row_mask:0xf bank_mask:0xf bound_ctrl:1
	v_pk_add_f32 v[122:123], v[26:27], -1.0 op_sel_hi:[1,0]
	v_add_f32_e32 v107, v88, v89
	v_add_f32_dpp v90, v90, v90 row_half_mirror row_mask:0xf bank_mask:0xf bound_ctrl:1
	ds_read_b128 v[72:75], v110 offset:20224
	v_pk_add_f32 v[124:125], v[28:29], -1.0 op_sel_hi:[1,0]
	v_add_f32_dpp v92, v90, v90 row_mirror row_mask:0xf bank_mask:0xf bound_ctrl:1
	v_pk_mul_f32 v[118:119], v[30:31], v[26:27]
	v_pk_fma_f32 v[2:3], v[92:93], v[42:43], v[82:83] op_sel_hi:[0,1,1] neg_lo:[1,0,0] neg_hi:[1,0,0]
	v_pk_fma_f32 v[4:5], v[92:93], v[44:45], v[84:85] op_sel_hi:[0,1,1] neg_lo:[1,0,0] neg_hi:[1,0,0]
	v_pk_fma_f32 v[122:123], v[6:7], v[122:123], 1.0 op_sel_hi:[1,1,0]
	s_waitcnt lgkmcnt(1)
	v_pk_mul_f32 v[86:87], v[2:3], v[60:61]
	v_pk_mul_f32 v[78:79], v[2:3], v[56:57]
	v_pk_fma_f32 v[86:87], v[4:5], v[62:63], v[86:87]
	v_pk_mul_f32 v[80:81], v[4:5], v[58:59]
	v_pk_mul_f32 v[88:89], v[2:3], v[50:51]
	v_add_f32_e32 v90, v86, v87
	v_pk_fma_f32 v[82:83], v[76:77], v[68:69], v[78:79] op_sel_hi:[0,1,1]
	v_pk_fma_f32 v[88:89], v[4:5], v[52:53], v[88:89]
	v_add_f32_dpp v90, v90, v90 quad_perm:[1,0,3,2] row_mask:0xf bank_mask:0xf bound_ctrl:1
	v_pk_fma_f32 v[84:85], v[76:77], v[70:71], v[80:81] op_sel_hi:[0,1,1]
	v_pk_fma_f32 v[124:125], v[8:9], v[124:125], 1.0 op_sel_hi:[1,1,0]
	v_add_f32_dpp v90, v90, v90 quad_perm:[2,3,0,1] row_mask:0xf bank_mask:0xf bound_ctrl:1
	v_pk_mul_f32 v[120:121], v[32:33], v[28:29]
	v_add_f32_e32 v108, v88, v89
	v_add_f32_dpp v90, v90, v90 row_half_mirror row_mask:0xf bank_mask:0xf bound_ctrl:1
	v_pk_mul_f32 v[122:123], v[14:15], v[122:123]
	v_pk_mul_f32 v[124:125], v[16:17], v[124:125]
	v_add_f32_dpp v92, v90, v90 row_mirror row_mask:0xf bank_mask:0xf bound_ctrl:1
	ds_write_b128 v112, v[22:25] offset:0
	ds_write_b128 v112, v[30:33] offset:4096
	v_pk_fma_f32 v[2:3], v[92:93], v[64:65], v[82:83] op_sel_hi:[0,1,1] neg_lo:[1,0,0] neg_hi:[1,0,0]
	v_pk_fma_f32 v[4:5], v[92:93], v[66:67], v[84:85] op_sel_hi:[0,1,1] neg_lo:[1,0,0] neg_hi:[1,0,0]
	ds_write_b128 v112, v[10:13] offset:16384
	s_waitcnt lgkmcnt(3)
	v_pk_mul_f32 v[88:89], v[2:3], v[72:73]
	ds_write_b128 v112, v[18:21] offset:20480
	v_pk_fma_f32 v[88:89], v[4:5], v[74:75], v[88:89]
	ds_write_b128 v112, v[118:121] offset:8192
	v_add_f32_e32 v109, v88, v89
	ds_write_b128 v112, v[122:125] offset:12288
	s_waitcnt lgkmcnt(0)
	v_xor_b32_e32 v110, 0x6000, v110
	v_xor_b32_e32 v111, 0x6000, v111
	v_xor_b32_e32 v112, 0x6000, v112
	s_add_i32 s33, s33, 1
	s_barrier
	s_branch .Lscan_chunk
